# scan staging waves: prefetched raw rows loaded straight into their home registers (24 register copies per chunk removed)
# baseline (speedup 1.0000x reference)
; #define LAS __attribute__((address_space(3)))
; __device__ __forceinline__ float row16_allsum(float x) { x = ROW_ROR_ADD(x, 8); x = ROW_ROR_ADD(x, 4); x = ROW_ROR_ADD(x, 2); x = ROW_ROR_ADD(x, 1); return x; }
; __device__ __forceinline__ f32x4 h4f(u32x2 r) { const h16x4 hv = __builtin_bit_cast(h16x4, r); return (f32x4){(float)hv[0], (float)hv[1], (float)hv[2], (float)hv[3]}; }
; __device__ __forceinline__ void scan_cvt_write(const Params& P, int h, const ScanRegs& R, LAS unsigned char* buf, int ll) {
;     const int sub = ll & 15, p = ll >> 4;
;     f32x4 f[5][2];
; #pragma unroll
;     for (int i = 0; i < 8; ++i) f[i >> 1][i & 1] = h4f(R.raw[i]);
;     { const f32x4 mu = *(const f32x4*)(P.in[I_MU] + h * 64 + 4 * sub), pm = b4f(R.rr[0]), p0 = b4f(R.rr[1]), p1 = b4f(R.rr[2]); f[4][0] = p0 + (pm - p0) * mu; f[4][1] = p1 + (p0 - p1) * mu; }
; #pragma unroll
;     for (int st = 0; st < 2; ++st) { f[0][st][0] = __expf(-f[0][st][0]); f[0][st][1] = __expf(-f[0][st][1]); f[0][st][2] = __expf(-f[0][st][2]); f[0][st][3] = __expf(-f[0][st][3]); }
;     LAS unsigned char* r0 = buf + (2 * p) * RECB + sub * 16; LAS unsigned char* r1 = r0 + RECB;
; #pragma unroll
;     for (int a = 0; a < 5; ++a) { *(LAS f32x4*)(r0 + a * 256) = f[a][0]; *(LAS f32x4*)(r1 + a * 256) = f[a][1]; }
;     *(LAS f32x4*)(r0 + 1344) = f[0][0] * f[2][1];
;     float be = (f[3][0][0] * f[2][1][0] + f[3][0][1] * f[2][1][1]) + (f[3][0][2] * f[2][1][2] + f[3][0][3] * f[2][1][3]);
;     float ka = (f[1][0][0] * f[2][1][0] + f[1][0][1] * f[2][1][1]) + (f[1][0][2] * f[2][1][2] + f[1][0][3] * f[2][1][3]);
;     be = row16_allsum(be); ka = row16_allsum(ka);
;     if (sub == 0) { typedef float f32x2v __attribute__((ext_vector_type(2))); *(LAS f32x2v*)(buf + (2 * p) * RECB + 1600) = (f32x2v){be, ka}; }
;     if (ll < 128) { const int t = ll >> 2, q = ll & 3; *(LAS f32x4*)(buf + t * RECB + 1280 + q * 16) = h4f(R.rv); }
; __device__ __forceinline__ void scan_phase(const Params& P, LAS unsigned char* lds, int tid, int wid, int lane) {
;     ...
;         for (int ck = 0; ck < NCK; ++ck) {
;             const int nsteps = (LPOS - TC * ck) < TC ? (LPOS - TC * ck) : TC;
;             if (wid >= 4) {
;                 if (ck + 1 < NCK) { scan_cvt_write(P, h, R, lds + ((ck + 1) & 1) * SBUF, ll); scan_gload(P, R, b, h, rg, ck + 2 < NCK ? ck + 2 : NCK - 1, ll); }
.LBB0_857:
	s_lshl_b64 s[8:9], s[0:1], 1
	s_add_u32 s31, s82, s8
	s_addc_u32 s37, s83, s9
	s_lshl_b64 s[12:13], s[90:91], 1
	s_add_u32 s36, s31, s12
	s_addc_u32 s37, s37, s13
	v_lshl_add_u64 v[92:93], v[54:55], 0, s[8:9]
	v_lshl_add_u64 v[94:95], v[56:57], 0, s[8:9]
	v_lshl_add_u64 v[96:97], v[58:59], 0, s[8:9]
	v_lshl_add_u64 v[98:99], v[60:61], 0, s[8:9]
	v_lshl_add_u64 v[100:101], v[52:53], 0, s[8:9]
	s_add_u32 s8, s92, s8
	s_addc_u32 s9, s93, s9
	s_waitcnt lgkmcnt(0)
	s_barrier
	s_add_u32 s8, s8, s12
	v_mov_b32_e32 v2, v0
	v_mov_b32_e32 v3, v0
	v_mov_b32_e32 v63, v0
	s_addc_u32 s9, s9, s13
	v_mov_b32_e32 v65, v0
	v_mov_b32_e32 v1, v0
	v_mov_b64_e32 v[4:5], v[2:3]
	v_lshl_add_u64 v[90:91], s[0:1], 2, v[50:51]
	v_lshl_add_u64 v[102:103], s[36:37], 0, v[62:63]
	v_lshl_add_u64 v[104:105], s[8:9], 0, v[64:65]
	s_mov_b32 s31, 0
	v_mov_b64_e32 v[2:3], v[0:1]
	s_waitcnt vmcnt(0) lgkmcnt(0)
	v_mov_b64_e32 v[66:67], v[12:13]
	v_mov_b64_e32 v[68:69], v[10:11]
	v_mov_b64_e32 v[70:71], v[8:9]
	v_mov_b64_e32 v[72:73], v[6:7]
	v_mov_b64_e32 v[74:75], v[20:21]
	v_mov_b64_e32 v[76:77], v[18:19]
	v_mov_b64_e32 v[78:79], v[16:17]
	v_mov_b64_e32 v[80:81], v[14:15]
	v_mov_b64_e32 v[82:83], v[22:23]
	v_mov_b64_e32 v[84:85], v[24:25]
	v_mov_b64_e32 v[86:87], v[28:29]
	v_mov_b64_e32 v[88:89], v[26:27]
	s_branch .LBB0_860
.LBB0_858:
	s_waitcnt vmcnt(0)
.LBB0_859:
	s_waitcnt lgkmcnt(0)
	s_barrier
	s_add_i32 s31, s31, 1
	s_cmpk_eq_i32 s31, 0x41
	s_cbranch_scc1 .LBB0_882
.LBB0_860:
	s_cmp_lg_u32 s31, 64
	s_cselect_b64 s[8:9], -1, 0
	s_andn2_b64 vcc, exec, s[72:73]
	s_mov_b64 s[12:13], -1
	s_cbranch_vccnz .LBB0_879
	s_andn2_b64 vcc, exec, s[8:9]
	s_cbranch_vccnz .LBB0_873
	global_load_dwordx4 v[6:9], v[90:91], off
	v_cvt_f32_f16_e32 v22, v66
	v_cvt_f32_f16_sdwa v23, v66 dst_sel:DWORD dst_unused:UNUSED_PAD src0_sel:WORD_1
	v_cvt_f32_f16_e32 v24, v67
	v_cvt_f32_f16_sdwa v25, v67 dst_sel:DWORD dst_unused:UNUSED_PAD src0_sel:WORD_1
	s_andn2_b32 s12, 1, s31
	v_cvt_f32_f16_e32 v26, v68
	v_cvt_f32_f16_sdwa v27, v68 dst_sel:DWORD dst_unused:UNUSED_PAD src0_sel:WORD_1
	v_cvt_f32_f16_e32 v28, v69
	v_cvt_f32_f16_sdwa v29, v69 dst_sel:DWORD dst_unused:UNUSED_PAD src0_sel:WORD_1
	v_cvt_f32_f16_sdwa v11, v72 dst_sel:DWORD dst_unused:UNUSED_PAD src0_sel:WORD_1
	v_cvt_f32_f16_e32 v10, v72
	v_cvt_f32_f16_sdwa v13, v73 dst_sel:DWORD dst_unused:UNUSED_PAD src0_sel:WORD_1
	v_cvt_f32_f16_e32 v12, v73
	s_mul_i32 s12, s12, 0xca00
	v_cvt_f32_f16_sdwa v15, v74 dst_sel:DWORD dst_unused:UNUSED_PAD src0_sel:WORD_1
	v_cvt_f32_f16_e32 v14, v74
	v_cvt_f32_f16_sdwa v17, v75 dst_sel:DWORD dst_unused:UNUSED_PAD src0_sel:WORD_1
	v_cvt_f32_f16_e32 v16, v75
	v_lshlrev_b32_e32 v1, 16, v82
	v_lshlrev_b32_e32 v30, 16, v84
	s_add_i32 s36, s12, 0
	v_cvt_f32_f16_sdwa v19, v80 dst_sel:DWORD dst_unused:UNUSED_PAD src0_sel:WORD_1
	v_cvt_f32_f16_e32 v18, v80
	v_cvt_f32_f16_sdwa v21, v81 dst_sel:DWORD dst_unused:UNUSED_PAD src0_sel:WORD_1
	v_cvt_f32_f16_e32 v20, v81
	v_and_b32_e32 v63, 0xffff0000, v82
	v_lshlrev_b32_e32 v65, 16, v83
	s_waitcnt lgkmcnt(2)
	v_and_b32_e32 v106, 0xffff0000, v83
	v_and_b32_e32 v31, 0xffff0000, v84
	v_lshlrev_b32_e32 v32, 16, v85
	v_and_b32_e32 v33, 0xffff0000, v85
	v_sub_f32_e32 v140, v1, v30
	v_add_u32_e32 v1, s36, v120
	v_mul_f32_e32 v22, 0xbfb8aa3b, v22
	v_mul_f32_e32 v23, 0xbfb8aa3b, v23
	v_mul_f32_e32 v24, 0xbfb8aa3b, v24
	v_mul_f32_e32 v25, 0xbfb8aa3b, v25
	v_lshlrev_b32_e32 v34, 16, v86
	v_and_b32_e32 v35, 0xffff0000, v86
	v_lshlrev_b32_e32 v36, 16, v87
	v_and_b32_e32 v37, 0xffff0000, v87
	v_cvt_f32_f16_e32 v39, v70
	v_cvt_f32_f16_sdwa v41, v70 dst_sel:DWORD dst_unused:UNUSED_PAD src0_sel:WORD_1
	v_cvt_f32_f16_e32 v43, v71
	v_cvt_f32_f16_sdwa v45, v71 dst_sel:DWORD dst_unused:UNUSED_PAD src0_sel:WORD_1
	v_sub_f32_e32 v141, v63, v31
	v_sub_f32_e32 v143, v106, v33
	v_sub_f32_e32 v142, v65, v32
	v_mul_f32_e32 v26, 0xbfb8aa3b, v26
	v_mul_f32_e32 v27, 0xbfb8aa3b, v27
	v_mul_f32_e32 v28, 0xbfb8aa3b, v28
	v_mul_f32_e32 v29, 0xbfb8aa3b, v29
	v_add_u32_e32 v63, v1, v48
	v_exp_f32_e32 v22, v22
	v_exp_f32_e32 v23, v23
	v_exp_f32_e32 v24, v24
	v_exp_f32_e32 v25, v25
	v_cvt_f32_f16_e32 v38, v76
	v_cvt_f32_f16_sdwa v40, v76 dst_sel:DWORD dst_unused:UNUSED_PAD src0_sel:WORD_1
	v_cvt_f32_f16_e32 v42, v77
	v_cvt_f32_f16_sdwa v44, v77 dst_sel:DWORD dst_unused:UNUSED_PAD src0_sel:WORD_1
	v_sub_f32_e32 v145, v31, v35
	v_sub_f32_e32 v144, v30, v34
	v_sub_f32_e32 v147, v33, v37
	v_sub_f32_e32 v146, v32, v36
	v_exp_f32_e32 v26, v26
	v_exp_f32_e32 v27, v27
	v_exp_f32_e32 v28, v28
	v_exp_f32_e32 v29, v29
	ds_write_b128 v63, v[10:13] offset:1872
	ds_write_b128 v63, v[14:17] offset:512
	ds_write_b128 v63, v[18:21] offset:2384
	ds_write_b128 v63, v[22:25]
	ds_write_b128 v63, v[26:29] offset:1616
	s_waitcnt lgkmcnt(6)
	v_cvt_f32_f16_e32 v110, v78
	v_cvt_f32_f16_sdwa v14, v79 dst_sel:DWORD dst_unused:UNUSED_PAD src0_sel:WORD_1
	v_mov_b32_e32 v15, v44
	v_mov_b32_e32 v111, v38
	s_waitcnt vmcnt(0)
; #define LAS __attribute__((address_space(3)))
; __device__ __forceinline__ void scan_gload(const Params& P, ScanRegs& R, int b, int h, int rg, int ck, int ll) {
;     const unsigned char* ws = P.ws;
;     const h16* arr[4] = {(const h16*)(ws + OFF_SE), (const h16*)(ws + OFF_SK), (const h16*)(ws + OFF_SKK), (const h16*)(ws + OFF_SB)};
;     const int sub = ll & 15, p = ll >> 4;
; #pragma unroll
;     for (int i = 0; i < 8; ++i) { const int t = 2 * p + (i & 1), a = i >> 1; int pos = TC * ck + t; pos = pos < LPOS ? pos : LPOS - 1;
;         R.raw[i] = *(const u32x2*)(arr[a] + (size_t)rowof(b, pos) * 512 + h * 64 + 4 * sub); }
;     { const bf16* PRb = (const bf16*)(ws + OFF_PR);
; #pragma unroll
;       for (int k = 0; k < 3; ++k) { const int pos = TC * ck + 2 * p - 1 + k; const int pc = pos < 0 ? 0 : (pos < LPOS ? pos : LPOS - 1);
;           const u32x2 v = *(const u32x2*)(PRb + (size_t)rowof(b, pc) * 512 + h * 64 + 4 * sub); R.rr[k] = pos < 0 ? (u32x2){0u, 0u} : v; } }
;     { const int l2 = ll & 127, t = l2 >> 2, q = l2 & 3; int pos = TC * ck + t; pos = pos < LPOS ? pos : LPOS - 1; R.rv = *(const u32x2*)((const h16*)(ws + OFF_SV) + (size_t)rowof(b, pos) * 512 + h * 64 + 16 * rg + 4 * q); }
; }
; __device__ __forceinline__ f32x4 h4f(u32x2 r) { const h16x4 hv = __builtin_bit_cast(h16x4, r); return (f32x4){(float)hv[0], (float)hv[1], (float)hv[2], (float)hv[3]}; }
; __device__ __forceinline__ f32x4 b4f(u32x2 r) { return (f32x4){__uint_as_float(r.x << 16), __uint_as_float(r.x & 0xffff0000u), __uint_as_float(r.y << 16), __uint_as_float(r.y & 0xffff0000u)}; }
; __device__ __forceinline__ void scan_cvt_write(const Params& P, int h, const ScanRegs& R, LAS unsigned char* buf, int ll) {
;     const int sub = ll & 15, p = ll >> 4;
;     f32x4 f[5][2];
; #pragma unroll
;     for (int i = 0; i < 8; ++i) f[i >> 1][i & 1] = h4f(R.raw[i]);
;     { const f32x4 mu = *(const f32x4*)(P.in[I_MU] + h * 64 + 4 * sub), pm = b4f(R.rr[0]), p0 = b4f(R.rr[1]), p1 = b4f(R.rr[2]); f[4][0] = p0 + (pm - p0) * mu; f[4][1] = p1 + (p0 - p1) * mu; }
; #pragma unroll
;     for (int st = 0; st < 2; ++st) { f[0][st][0] = __expf(-f[0][st][0]); f[0][st][1] = __expf(-f[0][st][1]); f[0][st][2] = __expf(-f[0][st][2]); f[0][st][3] = __expf(-f[0][st][3]); }
;     LAS unsigned char* r0 = buf + (2 * p) * RECB + sub * 16; LAS unsigned char* r1 = r0 + RECB;
; #pragma unroll
	v_pk_fma_f32 v[12:13], v[142:143], v[8:9], v[32:33]
	v_pk_fma_f32 v[10:11], v[140:141], v[6:7], v[30:31]
	v_pk_fma_f32 v[8:9], v[146:147], v[8:9], v[36:37]
	v_pk_fma_f32 v[6:7], v[144:145], v[6:7], v[34:35]
	ds_write_b128 v63, v[10:13] offset:1024
	ds_write_b128 v63, v[6:9] offset:2640
	v_cvt_f32_f16_sdwa v10, v78 dst_sel:DWORD dst_unused:UNUSED_PAD src0_sel:WORD_1
	v_cvt_f32_f16_e32 v12, v79
	v_mov_b32_e32 v6, v39
	v_mov_b32_e32 v7, v41
	v_mov_b32_e32 v8, v43
	v_mov_b32_e32 v9, v45
	ds_write_b128 v63, v[6:9] offset:256
	v_mov_b32_e32 v6, v38
	v_mov_b32_e32 v7, v40
	v_mov_b32_e32 v8, v42
	v_mov_b32_e32 v9, v44
	ds_write_b128 v63, v[6:9] offset:2128
	v_mov_b32_e32 v6, v110
	v_mov_b32_e32 v7, v10
	v_mov_b32_e32 v8, v12
	v_mov_b32_e32 v9, v14
	ds_write_b128 v63, v[6:9] offset:768
	v_mov_b32_e32 v6, v42
	v_mov_b32_e32 v7, v44
	v_pk_mul_f32 v[8:9], v[24:25], v[6:7]
	v_mov_b32_e32 v6, v38
	v_mov_b32_e32 v7, v40
	v_mov_b32_e32 v11, v40
	v_pk_mul_f32 v[6:7], v[22:23], v[6:7]
	v_mov_b32_e32 v13, v42
	ds_write_b128 v63, v[6:9] offset:1344
	v_pk_mul_f32 v[6:7], v[40:41], v[10:11]
	v_pk_mul_f32 v[8:9], v[44:45], v[14:15]
	v_pk_fma_f32 v[6:7], v[38:39], v[110:111], v[6:7]
	v_pk_fma_f32 v[8:9], v[42:43], v[12:13], v[8:9]
	s_nop 0
	v_pk_add_f32 v[6:7], v[6:7], v[8:9]
	v_mov_b32_e32 v8, v0
	v_mov_b32_e32 v9, v0
	s_nop 0
	v_mov_b32_dpp v8, v6 row_ror:8 row_mask:0xf bank_mask:0xf
	v_mov_b32_dpp v9, v7 row_ror:8 row_mask:0xf bank_mask:0xf
	v_pk_add_f32 v[6:7], v[6:7], v[8:9]
	v_mov_b32_e32 v8, v0
	v_mov_b32_e32 v9, v0
	s_nop 0
	v_mov_b32_dpp v8, v6 row_ror:4 row_mask:0xf bank_mask:0xf
	v_mov_b32_dpp v9, v7 row_ror:4 row_mask:0xf bank_mask:0xf
	v_pk_add_f32 v[6:7], v[6:7], v[8:9]
	v_mov_b32_e32 v8, v0
	v_mov_b32_e32 v9, v0
	s_nop 0
	v_mov_b32_dpp v8, v6 row_ror:2 row_mask:0xf bank_mask:0xf
	v_mov_b32_dpp v9, v7 row_ror:2 row_mask:0xf bank_mask:0xf
	v_pk_add_f32 v[6:7], v[6:7], v[8:9]
	v_mov_b32_e32 v8, v0
	v_mov_b32_e32 v9, v0
	s_nop 0
	v_mov_b32_dpp v8, v6 row_ror:1 row_mask:0xf bank_mask:0xf
	v_mov_b32_dpp v9, v7 row_ror:1 row_mask:0xf bank_mask:0xf
	s_and_saveexec_b64 s[12:13], s[20:21]
	v_pk_add_f32 v[6:7], v[6:7], v[8:9]
	ds_write_b64 v1, v[6:7] offset:1600
	s_or_b64 exec, exec, s[12:13]
	s_and_saveexec_b64 s[12:13], s[22:23]
	s_cbranch_execz .LBB0_866
	v_cvt_f32_f16_sdwa v7, v88 dst_sel:DWORD dst_unused:UNUSED_PAD src0_sel:WORD_1
	v_cvt_f32_f16_e32 v6, v88
	v_cvt_f32_f16_sdwa v9, v89 dst_sel:DWORD dst_unused:UNUSED_PAD src0_sel:WORD_1
	v_cvt_f32_f16_e32 v8, v89
	v_add3_u32 v1, s36, v123, v124
	ds_write_b128 v1, v[6:9] offset:1280
.LBB0_866:
	s_or_b64 exec, exec, s[12:13]
	s_min_u32 s12, s31, 62
	s_lshl_b32 s12, s12, 5
	s_add_i32 s36, s12, 64
	v_add_u32_e32 v26, s36, v107
	v_mov_b32_e32 v8, s30
	v_cmp_lt_i32_e32 vcc, 15, v26
	v_min_i32_e32 v1, 0x80f, v26
	v_add_u32_e32 v28, s12, v136
	v_cndmask_b32_e32 v6, v139, v8, vcc
	v_add_u32_e32 v6, v6, v1
	v_or_b32_e32 v1, 1, v26
	v_cmp_lt_i32_e32 vcc, 15, v1
	v_min_i32_e32 v9, 0x80f, v1
	v_ashrrev_i32_e32 v7, 31, v6
	v_cndmask_b32_e32 v1, v139, v8, vcc
	v_add_u32_e32 v8, v1, v9
	v_ashrrev_i32_e32 v9, 31, v8
	v_lshlrev_b64 v[14:15], 10, v[6:7]
	v_lshlrev_b64 v[16:17], 10, v[8:9]
	v_lshl_add_u64 v[6:7], v[92:93], 0, v[14:15]
	v_lshl_add_u64 v[8:9], v[92:93], 0, v[16:17]
	v_lshl_add_u64 v[10:11], v[94:95], 0, v[14:15]
	v_lshl_add_u64 v[12:13], v[94:95], 0, v[16:17]
	v_lshl_add_u64 v[18:19], v[96:97], 0, v[14:15]
	v_lshl_add_u64 v[20:21], v[96:97], 0, v[16:17]
	global_load_dwordx2 v[66:67], v[6:7], off
	s_nop 0
	global_load_dwordx2 v[68:69], v[8:9], off
	s_nop 0
	global_load_dwordx2 v[70:71], v[10:11], off
	s_nop 0
	global_load_dwordx2 v[72:73], v[12:13], off
	v_lshl_add_u64 v[22:23], v[98:99], 0, v[14:15]
	v_lshl_add_u64 v[24:25], v[98:99], 0, v[16:17]
	global_load_dwordx2 v[74:75], v[18:19], off
	global_load_dwordx2 v[76:77], v[20:21], off
	s_nop 0
	global_load_dwordx2 v[78:79], v[22:23], off
	global_load_dwordx2 v[80:81], v[24:25], off
	v_mov_b32_e32 v1, v0
	v_cmp_lt_i32_e32 vcc, -1, v28
	v_mov_b64_e32 v[82:83], v[0:1]
	s_and_saveexec_b64 s[12:13], vcc
	s_cbranch_execz .LBB0_868
	v_min_u32_e32 v22, 0x80f, v28
	v_or_b32_e32 v23, 0x4000, v22
	v_add_u32_e32 v22, s30, v22
	v_cmp_gt_u32_e32 vcc, 16, v28
	s_nop 1
	v_cndmask_b32_e32 v22, v22, v23, vcc
	v_ashrrev_i32_e32 v23, 31, v22
	v_lshlrev_b64 v[22:23], 10, v[22:23]
	v_lshl_add_u64 v[22:23], v[100:101], 0, v[22:23]
	global_load_dwordx2 v[82:83], v[22:23], off
.LBB0_868:
	s_or_b64 exec, exec, s[12:13]
	v_cmp_lt_i32_e32 vcc, -1, v26
	v_mov_b64_e32 v[84:85], v[0:1]
	s_and_saveexec_b64 s[12:13], vcc
	s_cbranch_execz .LBB0_870
	v_min_u32_e32 v1, 0x80f, v26
	v_or_b32_e32 v24, 0x4000, v1
	v_add_u32_e32 v1, s30, v1
	v_cmp_gt_u32_e32 vcc, 16, v26
	s_nop 1
	v_cndmask_b32_e32 v24, v1, v24, vcc
	v_ashrrev_i32_e32 v25, 31, v24
	v_lshlrev_b64 v[24:25], 10, v[24:25]
	v_lshl_add_u64 v[24:25], v[100:101], 0, v[24:25]
	global_load_dwordx2 v[84:85], v[24:25], off
.LBB0_870:
	s_or_b64 exec, exec, s[12:13]
	v_mov_b32_e32 v1, v0
	v_cmp_lt_i32_e32 vcc, -3, v28
	v_mov_b64_e32 v[86:87], v[0:1]
	s_and_saveexec_b64 s[12:13], vcc
	s_cbranch_execz .LBB0_872
	v_add_u32_e32 v1, 2, v28
	v_min_u32_e32 v1, 0x80f, v1
	v_or_b32_e32 v26, 0x4000, v1
	v_add_u32_e32 v1, s30, v1
	v_cmp_gt_i32_e32 vcc, 14, v28
	s_nop 1
	v_cndmask_b32_e32 v26, v1, v26, vcc
	v_ashrrev_i32_e32 v27, 31, v26
	v_lshlrev_b64 v[26:27], 10, v[26:27]
	v_lshl_add_u64 v[26:27], v[100:101], 0, v[26:27]
	global_load_dwordx2 v[86:87], v[26:27], off
.LBB0_872:
	s_or_b64 exec, exec, s[12:13]
	v_or_b32_e32 v1, s36, v119
	v_min_u32_e32 v1, 0x80f, v1
	v_add_u32_e32 v28, s30, v1
	v_ashrrev_i32_e32 v29, 31, v28
	v_lshlrev_b64 v[28:29], 10, v[28:29]
	v_lshl_add_u64 v[28:29], v[102:103], 0, v[28:29]
	global_load_dwordx2 v[88:89], v[28:29], off
	s_cmp_lg_u32 s31, 0
	s_cselect_b64 s[12:13], -1, 0
